# prompt diff-attn finalize: sub-LN gain loads batched; GDN chunk recurrence: per-chunk operand staging replaced by 7 loads in flight issued before the chunk barrier
# speedup vs baseline: 1.1525x; 1.0216x over previous
.LBB0_1088:
	s_and_b64 vcc, exec, s[0:1]
	s_barrier
	s_cbranch_vccnz .LBB0_1090
	v_lshl_add_u64 v[48:49], s[96:97], 0, v[130:131]
	s_lshl_b32 s26, s10, 1
	v_lshl_add_u64 v[54:55], v[48:49], 0, s[26:27]
	v_cmp_gt_f32_e32 vcc, s6, v50
	v_mul_f32_e32 v48, 0x4b800000, v50
	v_readlane_b32 s64, v253, 37
	v_cndmask_b32_e32 v48, v50, v48, vcc
	v_rsq_f32_e32 v48, v48
	v_readlane_b32 s78, v253, 51
	v_readlane_b32 s79, v253, 52
	v_lshlrev_b32_e32 v124, 1, v138
	v_mul_f32_e32 v49, 0x45800000, v48
	v_cndmask_b32_e32 v48, v48, v49, vcc
	v_lshlrev_b32_e32 v49, 2, v138
	v_mul_f32_e32 v48, 0x3f4ccccd, v48
	global_load_dwordx4 v[50:53], v49, s[78:79]
	global_load_dwordx4 v[168:171], v49, s[78:79] offset:64
	global_load_dwordx4 v[172:175], v49, s[78:79] offset:128
	global_load_dwordx4 v[176:179], v49, s[78:79] offset:192
	global_load_dwordx4 v[180:183], v49, s[78:79] offset:256
	global_load_dwordx4 v[184:187], v49, s[78:79] offset:320
	global_load_dwordx4 v[188:191], v49, s[78:79] offset:384
	global_load_dwordx4 v[192:195], v49, s[78:79] offset:448
	global_load_dwordx4 v[196:199], v49, s[78:79] offset:512
	global_load_dwordx4 v[200:203], v49, s[78:79] offset:576
	global_load_dwordx4 v[204:207], v49, s[78:79] offset:640
	global_load_dwordx4 v[208:211], v49, s[78:79] offset:704
	global_load_dwordx4 v[212:215], v49, s[78:79] offset:768
	global_load_dwordx4 v[216:219], v49, s[78:79] offset:832
	global_load_dwordx4 v[220:223], v49, s[78:79] offset:896
	global_load_dwordx4 v[224:227], v49, s[78:79] offset:960
	s_waitcnt vmcnt(0)
	v_pk_mul_f32 v[56:57], v[108:109], v[48:49] op_sel_hi:[1,0]
	v_pk_mul_f32 v[58:59], v[110:111], v[48:49] op_sel_hi:[1,0]
	v_pk_mul_f32 v[44:45], v[44:45], v[48:49] op_sel_hi:[1,0]
	v_pk_mul_f32 v[46:47], v[46:47], v[48:49] op_sel_hi:[1,0]
	v_pk_mul_f32 v[40:41], v[40:41], v[48:49] op_sel_hi:[1,0]
	v_pk_mul_f32 v[42:43], v[42:43], v[48:49] op_sel_hi:[1,0]
	v_pk_mul_f32 v[36:37], v[36:37], v[48:49] op_sel_hi:[1,0]
	v_pk_mul_f32 v[38:39], v[38:39], v[48:49] op_sel_hi:[1,0]
	v_pk_mul_f32 v[32:33], v[32:33], v[48:49] op_sel_hi:[1,0]
	v_pk_mul_f32 v[34:35], v[34:35], v[48:49] op_sel_hi:[1,0]
	v_pk_mul_f32 v[28:29], v[28:29], v[48:49] op_sel_hi:[1,0]
	v_pk_mul_f32 v[30:31], v[30:31], v[48:49] op_sel_hi:[1,0]
	v_pk_mul_f32 v[24:25], v[24:25], v[48:49] op_sel_hi:[1,0]
	v_pk_mul_f32 v[26:27], v[26:27], v[48:49] op_sel_hi:[1,0]
	v_pk_mul_f32 v[20:21], v[20:21], v[48:49] op_sel_hi:[1,0]
	v_pk_mul_f32 v[22:23], v[22:23], v[48:49] op_sel_hi:[1,0]
	v_pk_mul_f32 v[16:17], v[16:17], v[48:49] op_sel_hi:[1,0]
	v_pk_mul_f32 v[18:19], v[18:19], v[48:49] op_sel_hi:[1,0]
	v_pk_mul_f32 v[12:13], v[12:13], v[48:49] op_sel_hi:[1,0]
	v_pk_mul_f32 v[14:15], v[14:15], v[48:49] op_sel_hi:[1,0]
	v_pk_mul_f32 v[8:9], v[8:9], v[48:49] op_sel_hi:[1,0]
	v_pk_mul_f32 v[10:11], v[10:11], v[48:49] op_sel_hi:[1,0]
	v_pk_mul_f32 v[0:1], v[0:1], v[48:49] op_sel_hi:[1,0]
	v_pk_mul_f32 v[2:3], v[2:3], v[48:49] op_sel_hi:[1,0]
	v_pk_mul_f32 v[6:7], v[6:7], v[48:49] op_sel_hi:[1,0]
	v_pk_mul_f32 v[4:5], v[4:5], v[48:49] op_sel_hi:[1,0]
	v_readlane_b32 s65, v253, 38
	v_readlane_b32 s66, v253, 39
	v_readlane_b32 s67, v253, 40
	v_readlane_b32 s68, v253, 41
	v_readlane_b32 s69, v253, 42
	v_readlane_b32 s70, v253, 43
	v_readlane_b32 s71, v253, 44
	v_readlane_b32 s72, v253, 45
	v_readlane_b32 s73, v253, 46
	v_readlane_b32 s74, v253, 47
	v_readlane_b32 s75, v253, 48
	v_readlane_b32 s76, v253, 49
	v_readlane_b32 s77, v253, 50
	v_pk_mul_f32 v[52:53], v[58:59], v[52:53]
	v_pk_mul_f32 v[50:51], v[56:57], v[50:51]
	v_cvt_pk_bf16_f32 v57, v52, v53
	v_cvt_pk_bf16_f32 v56, v50, v51
	v_lshl_add_u64 v[50:51], v[54:55], 0, v[124:125]
	v_pk_mul_f32 v[58:59], v[106:107], v[48:49] op_sel_hi:[1,0]
	global_store_dwordx2 v[50:51], v[56:57], off
	v_pk_mul_f32 v[56:57], v[104:105], v[48:49] op_sel_hi:[1,0]
	v_pk_mul_f32 v[54:55], v[58:59], v[170:171]
	v_pk_mul_f32 v[52:53], v[56:57], v[168:169]
	v_pk_mul_f32 v[56:57], v[100:101], v[48:49] op_sel_hi:[1,0]
	v_cvt_pk_bf16_f32 v52, v52, v53
	v_cvt_pk_bf16_f32 v53, v54, v55
	global_store_dwordx2 v[50:51], v[52:53], off offset:32
	v_pk_mul_f32 v[58:59], v[102:103], v[48:49] op_sel_hi:[1,0]
	v_pk_mul_f32 v[52:53], v[56:57], v[172:173]
	v_pk_mul_f32 v[54:55], v[58:59], v[174:175]
	v_cvt_pk_bf16_f32 v52, v52, v53
	v_cvt_pk_bf16_f32 v53, v54, v55
	global_store_dwordx2 v[50:51], v[52:53], off offset:64
	v_pk_mul_f32 v[56:57], v[92:93], v[48:49] op_sel_hi:[1,0]
	v_pk_mul_f32 v[58:59], v[94:95], v[48:49] op_sel_hi:[1,0]
	v_pk_mul_f32 v[52:53], v[56:57], v[176:177]
	v_pk_mul_f32 v[54:55], v[58:59], v[178:179]
	v_cvt_pk_bf16_f32 v52, v52, v53
	v_cvt_pk_bf16_f32 v53, v54, v55
	global_store_dwordx2 v[50:51], v[52:53], off offset:96
	v_pk_mul_f32 v[46:47], v[46:47], v[182:183]
	v_pk_mul_f32 v[44:45], v[44:45], v[180:181]
	s_nop 0
	v_cvt_pk_bf16_f32 v44, v44, v45
	v_cvt_pk_bf16_f32 v45, v46, v47
	global_store_dwordx2 v[50:51], v[44:45], off offset:128
	v_pk_mul_f32 v[42:43], v[42:43], v[186:187]
	v_pk_mul_f32 v[40:41], v[40:41], v[184:185]
	s_nop 0
	v_cvt_pk_bf16_f32 v40, v40, v41
	v_cvt_pk_bf16_f32 v41, v42, v43
	global_store_dwordx2 v[50:51], v[40:41], off offset:160
	v_pk_mul_f32 v[38:39], v[38:39], v[190:191]
	v_pk_mul_f32 v[36:37], v[36:37], v[188:189]
	s_nop 0
	v_cvt_pk_bf16_f32 v36, v36, v37
	v_cvt_pk_bf16_f32 v37, v38, v39
	global_store_dwordx2 v[50:51], v[36:37], off offset:192
	v_pk_mul_f32 v[34:35], v[34:35], v[194:195]
	v_pk_mul_f32 v[32:33], v[32:33], v[192:193]
	s_nop 0
	v_cvt_pk_bf16_f32 v32, v32, v33
	v_cvt_pk_bf16_f32 v33, v34, v35
	global_store_dwordx2 v[50:51], v[32:33], off offset:224
	v_pk_mul_f32 v[30:31], v[30:31], v[198:199]
	v_pk_mul_f32 v[28:29], v[28:29], v[196:197]
	s_nop 0
	v_cvt_pk_bf16_f32 v28, v28, v29
	v_cvt_pk_bf16_f32 v29, v30, v31
	global_store_dwordx2 v[50:51], v[28:29], off offset:256
	v_pk_mul_f32 v[26:27], v[26:27], v[202:203]
	v_pk_mul_f32 v[24:25], v[24:25], v[200:201]
	s_nop 0
	v_cvt_pk_bf16_f32 v24, v24, v25
	v_cvt_pk_bf16_f32 v25, v26, v27
	global_store_dwordx2 v[50:51], v[24:25], off offset:288
	v_pk_mul_f32 v[22:23], v[22:23], v[206:207]
	v_pk_mul_f32 v[20:21], v[20:21], v[204:205]
	s_nop 0
	v_cvt_pk_bf16_f32 v20, v20, v21
	v_cvt_pk_bf16_f32 v21, v22, v23
	global_store_dwordx2 v[50:51], v[20:21], off offset:320
	v_pk_mul_f32 v[18:19], v[18:19], v[210:211]
	v_pk_mul_f32 v[16:17], v[16:17], v[208:209]
	s_nop 0
	v_cvt_pk_bf16_f32 v16, v16, v17
	v_cvt_pk_bf16_f32 v17, v18, v19
	global_store_dwordx2 v[50:51], v[16:17], off offset:352
	v_pk_mul_f32 v[14:15], v[14:15], v[214:215]
	v_pk_mul_f32 v[12:13], v[12:13], v[212:213]
	s_nop 0
	v_cvt_pk_bf16_f32 v12, v12, v13
	v_cvt_pk_bf16_f32 v13, v14, v15
	global_store_dwordx2 v[50:51], v[12:13], off offset:384
	v_pk_mul_f32 v[10:11], v[10:11], v[218:219]
	v_pk_mul_f32 v[8:9], v[8:9], v[216:217]
	s_nop 0
	v_cvt_pk_bf16_f32 v8, v8, v9
	v_cvt_pk_bf16_f32 v9, v10, v11
	global_store_dwordx2 v[50:51], v[8:9], off offset:416
	v_pk_mul_f32 v[2:3], v[2:3], v[222:223]
	v_pk_mul_f32 v[0:1], v[0:1], v[220:221]
	s_nop 0
	v_cvt_pk_bf16_f32 v0, v0, v1
	v_cvt_pk_bf16_f32 v1, v2, v3
	global_store_dwordx2 v[50:51], v[0:1], off offset:448
	v_pk_mul_f32 v[2:3], v[4:5], v[226:227]
	v_pk_mul_f32 v[0:1], v[6:7], v[224:225]
	s_nop 0
	v_cvt_pk_bf16_f32 v0, v0, v1
	v_cvt_pk_bf16_f32 v1, v2, v3
	global_store_dwordx2 v[50:51], v[0:1], off offset:480

.LBB0_1098:
	s_lshl_b32 s10, s0, 4
	s_add_i32 s10, s1, s10
	s_ashr_i32 s11, s10, 31
	s_mul_i32 s29, s10, 0x12000
	s_mul_hi_i32 s26, s10, 0x12000
	s_add_u32 s30, s19, s29
	s_addc_u32 s31, s42, s26
	s_lshl_b64 s[10:11], s[10:11], 2
	s_add_u32 s10, s43, s10
	s_addc_u32 s11, s4, s11
	global_load_dword v56, v125, s[10:11] sc1
	v_add_u32_e32 v40, 0x2000, v113
	v_add_u32_e32 v41, 0x8000, v113
	v_add_u32_e32 v38, 0xa000, v113
	v_add_u32_e32 v39, 0xc000, v113
	v_add_u32_e32 v34, 0xe000, v113
	v_add_u32_e32 v35, 0x10000, v113
	global_load_dwordx4 v[166:169], v113, s[30:31]
	global_load_dwordx4 v[170:173], v40, s[30:31]
	global_load_dwordx4 v[174:177], v41, s[30:31]
	global_load_dwordx4 v[178:181], v38, s[30:31]
	global_load_dwordx4 v[182:185], v39, s[30:31]
	global_load_dwordx4 v[186:189], v34, s[30:31]
	global_load_dwordx4 v[190:193], v35, s[30:31]
	v_ashrrev_i32_e32 v32, 4, v67
	v_mul_u32_u24_e32 v32, 0x110, v32
	v_and_b32_e32 v33, 15, v67
	v_lshl_add_u32 v32, v33, 4, v32
	v_ashrrev_i32_e32 v33, 3, v67
	v_lshl_add_u32 v33, v33, 4, v113
	s_waitcnt lgkmcnt(0)
	s_barrier
	s_waitcnt vmcnt(6)
	ds_write_b128 v32, v[166:169] offset:0
	s_waitcnt vmcnt(5)
	ds_write_b128 v32, v[170:173] offset:8704
	s_waitcnt vmcnt(4)
	ds_write_b128 v32, v[174:177] offset:17408
	s_waitcnt vmcnt(3)
	ds_write_b128 v32, v[178:181] offset:26112
	s_waitcnt vmcnt(2)
	ds_write_b128 v33, v[182:185] offset:34816
	s_waitcnt vmcnt(1)
	ds_write_b128 v33, v[186:189] offset:44032
	s_waitcnt vmcnt(0)
	ds_write_b128 v33, v[190:193] offset:53248
	v_lshl_add_u64 v[32:33], s[30:31], 0, v[72:73]
	v_lshl_add_u64 v[32:33], v[32:33], 0, v[68:69]
	s_mov_b64 s[10:11], 0x4000
	v_lshl_add_u64 v[36:37], v[32:33], 0, s[10:11]
	v_add_co_u32_e32 v32, vcc, 0x4000, v32
	v_add_u32_e32 v57, v110, v68
	s_nop 0
	v_addc_co_u32_e32 v33, vcc, 0, v33, vcc
	global_load_dwordx2 v[62:63], v[32:33], off
	global_load_dwordx2 v[76:77], v[36:37], off offset:32
	global_load_dwordx2 v[34:35], v[36:37], off offset:64
	s_nop 0
	global_load_dwordx2 v[32:33], v[36:37], off offset:96
	v_add_u32_e32 v36, v66, v109
	s_waitcnt lgkmcnt(0)
	s_barrier
	ds_read_b128 v[52:55], v36 offset:62464
	ds_read_b128 v[48:51], v36 offset:62528
	ds_read_b128 v[44:47], v36 offset:62592
	ds_read_b128 v[40:43], v36 offset:62656
	ds_read_b128 v[36:39], v114
	ds_read_b128 v[58:61], v114 offset:64
	s_waitcnt lgkmcnt(1)
	v_mfma_f32_16x16x32_bf16 v[36:39], v[36:39], v[52:55], 0
	s_waitcnt lgkmcnt(0)
	v_mfma_f32_16x16x32_bf16 v[36:39], v[58:61], v[48:51], v[36:39]
	ds_read_b128 v[58:61], v114 offset:128
	s_waitcnt lgkmcnt(0)
	v_mfma_f32_16x16x32_bf16 v[36:39], v[58:61], v[44:47], v[36:39]
	ds_read_b128 v[58:61], v114 offset:192
	s_waitcnt lgkmcnt(0)
	v_mfma_f32_16x16x32_bf16 v[36:39], v[58:61], v[40:43], v[36:39]
	s_waitcnt vmcnt(3)
	v_lshlrev_b32_e32 v58, 16, v62
	v_and_b32_e32 v59, 0xffff0000, v62
	s_nop 4
	v_pk_add_f32 v[36:37], v[58:59], v[36:37] neg_lo:[0,1] neg_hi:[0,1]
	v_lshlrev_b32_e32 v58, 16, v63
	v_and_b32_e32 v59, 0xffff0000, v63
	v_pk_add_f32 v[38:39], v[58:59], v[38:39] neg_lo:[0,1] neg_hi:[0,1]
	v_cvt_pk_bf16_f32 v36, v36, v37
	v_cvt_pk_bf16_f32 v37, v38, v39
	ds_write_b64 v57, v[36:37]
	ds_read_b128 v[36:39], v114 offset:4352
	ds_read_b128 v[58:61], v114 offset:4416
	s_waitcnt lgkmcnt(1)
	v_mfma_f32_16x16x32_bf16 v[36:39], v[36:39], v[52:55], 0
	s_waitcnt lgkmcnt(0)
	v_mfma_f32_16x16x32_bf16 v[36:39], v[58:61], v[48:51], v[36:39]
	ds_read_b128 v[58:61], v114 offset:4480
	s_waitcnt lgkmcnt(0)
	v_mfma_f32_16x16x32_bf16 v[36:39], v[58:61], v[44:47], v[36:39]
	ds_read_b128 v[58:61], v114 offset:4544
	s_waitcnt lgkmcnt(0)
	v_mfma_f32_16x16x32_bf16 v[36:39], v[58:61], v[40:43], v[36:39]
	s_waitcnt vmcnt(2)
	v_lshlrev_b32_e32 v58, 16, v76
	v_and_b32_e32 v59, 0xffff0000, v76
	s_nop 4
	v_pk_add_f32 v[36:37], v[58:59], v[36:37] neg_lo:[0,1] neg_hi:[0,1]
	v_lshlrev_b32_e32 v58, 16, v77
	v_and_b32_e32 v59, 0xffff0000, v77
	v_pk_add_f32 v[38:39], v[58:59], v[38:39] neg_lo:[0,1] neg_hi:[0,1]
	v_cvt_pk_bf16_f32 v36, v36, v37
	v_cvt_pk_bf16_f32 v37, v38, v39
	ds_write_b64 v57, v[36:37] offset:32
	ds_read_b128 v[36:39], v114 offset:8704
	ds_read_b128 v[58:61], v114 offset:8768
	s_waitcnt lgkmcnt(1)
	v_mfma_f32_16x16x32_bf16 v[36:39], v[36:39], v[52:55], 0
	s_waitcnt lgkmcnt(0)
	v_mfma_f32_16x16x32_bf16 v[36:39], v[58:61], v[48:51], v[36:39]
	ds_read_b128 v[58:61], v114 offset:8832
	s_waitcnt lgkmcnt(0)
	v_mfma_f32_16x16x32_bf16 v[36:39], v[58:61], v[44:47], v[36:39]
	ds_read_b128 v[58:61], v114 offset:8896
	s_waitcnt lgkmcnt(0)
	v_mfma_f32_16x16x32_bf16 v[36:39], v[58:61], v[40:43], v[36:39]
	s_waitcnt vmcnt(1)
	v_lshlrev_b32_e32 v58, 16, v34
	v_and_b32_e32 v59, 0xffff0000, v34
	v_lshlrev_b32_e32 v34, 16, v35
	v_and_b32_e32 v35, 0xffff0000, v35
	s_nop 2
	v_pk_add_f32 v[36:37], v[58:59], v[36:37] neg_lo:[0,1] neg_hi:[0,1]
	v_pk_add_f32 v[34:35], v[34:35], v[38:39] neg_lo:[0,1] neg_hi:[0,1]
	v_cvt_pk_bf16_f32 v36, v36, v37
	v_cvt_pk_bf16_f32 v37, v34, v35
	ds_write_b64 v57, v[36:37] offset:64
	ds_read_b128 v[34:37], v114 offset:13056
	ds_read_b128 v[58:61], v114 offset:13120
	s_waitcnt lgkmcnt(1)
	v_mfma_f32_16x16x32_bf16 v[34:37], v[34:37], v[52:55], 0
	s_waitcnt vmcnt(0)
	v_lshlrev_b32_e32 v38, 16, v32
	v_and_b32_e32 v39, 0xffff0000, v32
	v_lshlrev_b32_e32 v32, 16, v33
	s_waitcnt lgkmcnt(0)
	v_mfma_f32_16x16x32_bf16 v[34:37], v[58:61], v[48:51], v[34:37]
	ds_read_b128 v[58:61], v114 offset:13184
	v_and_b32_e32 v33, 0xffff0000, v33
	s_waitcnt lgkmcnt(0)
	v_mfma_f32_16x16x32_bf16 v[34:37], v[58:61], v[44:47], v[34:37]
	ds_read_b128 v[58:61], v114 offset:13248
	s_waitcnt lgkmcnt(0)
	v_mfma_f32_16x16x32_bf16 v[34:37], v[58:61], v[40:43], v[34:37]
	s_nop 7
	v_pk_add_f32 v[34:35], v[38:39], v[34:35] neg_lo:[0,1] neg_hi:[0,1]
	v_pk_add_f32 v[32:33], v[32:33], v[36:37] neg_lo:[0,1] neg_hi:[0,1]
	v_cvt_pk_bf16_f32 v34, v34, v35
	v_cvt_pk_bf16_f32 v35, v32, v33
	v_add_u32_e32 v32, v110, v109
	ds_write_b64 v57, v[34:35] offset:96
	s_waitcnt lgkmcnt(0)
	s_barrier
	ds_read_b128 v[36:39], v32
	ds_read_b128 v[32:35], v32 offset:64
	ds_read_b128 v[58:61], v114 offset:17408
	ds_read_b128 v[76:79], v114 offset:17472
	s_waitcnt lgkmcnt(1)
	v_mfma_f32_16x16x32_bf16 v[58:61], v[58:61], v[52:55], 0
	s_waitcnt lgkmcnt(0)
	v_mfma_f32_16x16x32_bf16 v[58:61], v[76:79], v[48:51], v[58:61]
	ds_read_b128 v[76:79], v114 offset:17536
	s_waitcnt lgkmcnt(0)
	v_mfma_f32_16x16x32_bf16 v[58:61], v[76:79], v[44:47], v[58:61]
	ds_read_b128 v[76:79], v114 offset:17600
	s_waitcnt lgkmcnt(0)
	v_mfma_f32_16x16x32_bf16 v[58:61], v[76:79], v[40:43], v[58:61]
	ds_read_b128 v[76:79], v115 offset:34816
	s_waitcnt lgkmcnt(0)
	v_mfma_f32_16x16x32_bf16 v[58:61], v[76:79], v[36:39], v[58:61]
	ds_read_b128 v[76:79], v115 offset:34880
	s_waitcnt lgkmcnt(0)
	v_mfma_f32_16x16x32_bf16 v[58:61], v[76:79], v[32:35], v[58:61]
	s_nop 7
	v_cvt_pk_bf16_f32 v57, v58, s0
	ds_write_b16 v116, v57
	v_cvt_pk_bf16_f32 v57, v59, s0
	ds_write_b16 v117, v57
	v_cvt_pk_bf16_f32 v57, v60, s0
	ds_write_b16 v117, v57 offset:272
	v_cvt_pk_bf16_f32 v57, v61, s0
	ds_write_b16 v117, v57 offset:544
	ds_read_b128 v[58:61], v114 offset:21760
	ds_read_b128 v[76:79], v114 offset:21824
	s_waitcnt lgkmcnt(1)
	v_mfma_f32_16x16x32_bf16 v[58:61], v[58:61], v[52:55], 0
	s_waitcnt lgkmcnt(0)
	v_mfma_f32_16x16x32_bf16 v[58:61], v[76:79], v[48:51], v[58:61]
	ds_read_b128 v[76:79], v114 offset:21888
	s_waitcnt lgkmcnt(0)
	v_mfma_f32_16x16x32_bf16 v[58:61], v[76:79], v[44:47], v[58:61]
	ds_read_b128 v[76:79], v114 offset:21952
	s_waitcnt lgkmcnt(0)
	v_mfma_f32_16x16x32_bf16 v[58:61], v[76:79], v[40:43], v[58:61]
	ds_read_b128 v[76:79], v115 offset:37120
	s_waitcnt lgkmcnt(0)
	v_mfma_f32_16x16x32_bf16 v[58:61], v[76:79], v[36:39], v[58:61]
	ds_read_b128 v[76:79], v115 offset:37184
	s_waitcnt lgkmcnt(0)
	v_mfma_f32_16x16x32_bf16 v[58:61], v[76:79], v[32:35], v[58:61]
	s_nop 7
	v_cvt_pk_bf16_f32 v57, v58, s0
	ds_write_b16 v117, v57 offset:4080
	v_cvt_pk_bf16_f32 v57, v59, s0
	ds_write_b16 v117, v57 offset:4352
	v_cvt_pk_bf16_f32 v57, v60, s0
	ds_write_b16 v117, v57 offset:4624
	v_cvt_pk_bf16_f32 v57, v61, s0
	ds_write_b16 v117, v57 offset:4896
	ds_read_b128 v[58:61], v114 offset:26112
	ds_read_b128 v[76:79], v114 offset:26176
	s_waitcnt lgkmcnt(1)
	v_mfma_f32_16x16x32_bf16 v[58:61], v[58:61], v[52:55], 0
	s_waitcnt lgkmcnt(0)
	v_mfma_f32_16x16x32_bf16 v[58:61], v[76:79], v[48:51], v[58:61]
	ds_read_b128 v[76:79], v114 offset:26240
	s_waitcnt lgkmcnt(0)
	v_mfma_f32_16x16x32_bf16 v[58:61], v[76:79], v[44:47], v[58:61]
	ds_read_b128 v[76:79], v114 offset:26304
	s_waitcnt lgkmcnt(0)
	v_mfma_f32_16x16x32_bf16 v[58:61], v[76:79], v[40:43], v[58:61]
	ds_read_b128 v[76:79], v115 offset:39424
	s_waitcnt lgkmcnt(0)
	v_mfma_f32_16x16x32_bf16 v[58:61], v[76:79], v[36:39], v[58:61]
	ds_read_b128 v[76:79], v115 offset:39488
	s_waitcnt lgkmcnt(0)
	v_mfma_f32_16x16x32_bf16 v[58:61], v[76:79], v[32:35], v[58:61]
	s_nop 7
	v_cvt_pk_bf16_f32 v57, v58, s0
	ds_write_b16 v117, v57 offset:8432
	v_cvt_pk_bf16_f32 v57, v59, s0
	ds_write_b16 v117, v57 offset:8704
	v_cvt_pk_bf16_f32 v57, v60, s0
	ds_write_b16 v117, v57 offset:8976
	v_cvt_pk_bf16_f32 v57, v61, s0
	ds_write_b16 v117, v57 offset:9248
	ds_read_b128 v[58:61], v114 offset:30464
	s_waitcnt lgkmcnt(0)
	v_mfma_f32_16x16x32_bf16 v[52:55], v[58:61], v[52:55], 0
	ds_read_b128 v[58:61], v114 offset:30528
	v_pk_mul_f32 v[30:31], v[30:31], v[56:57] op_sel_hi:[1,0]
	v_pk_mul_f32 v[28:29], v[28:29], v[56:57] op_sel_hi:[1,0]
	s_waitcnt lgkmcnt(0)
	v_mfma_f32_16x16x32_bf16 v[48:51], v[58:61], v[48:51], v[52:55]
	s_nop 2
	ds_read_b128 v[52:55], v114 offset:30592
	v_pk_mul_f32 v[22:23], v[22:23], v[56:57] op_sel_hi:[1,0]
	v_pk_mul_f32 v[20:21], v[20:21], v[56:57] op_sel_hi:[1,0]
	s_waitcnt lgkmcnt(0)
	v_mfma_f32_16x16x32_bf16 v[44:47], v[52:55], v[44:47], v[48:51]
	s_nop 2
	ds_read_b128 v[48:51], v114 offset:30656
	v_pk_mul_f32 v[2:3], v[2:3], v[56:57] op_sel_hi:[1,0]
	v_pk_mul_f32 v[0:1], v[0:1], v[56:57] op_sel_hi:[1,0]
	s_waitcnt lgkmcnt(0)
	v_mfma_f32_16x16x32_bf16 v[40:43], v[48:51], v[40:43], v[44:47]
	s_nop 2
	ds_read_b128 v[44:47], v115 offset:41728
	v_pk_mul_f32 v[18:19], v[18:19], v[56:57] op_sel_hi:[1,0]
	v_pk_mul_f32 v[16:17], v[16:17], v[56:57] op_sel_hi:[1,0]
	s_waitcnt lgkmcnt(0)
	v_mfma_f32_16x16x32_bf16 v[40:43], v[44:47], v[36:39], v[40:43]
	ds_read_b128 v[44:47], v115 offset:41792
	v_pk_mul_f32 v[6:7], v[6:7], v[56:57] op_sel_hi:[1,0]
	v_pk_mul_f32 v[4:5], v[4:5], v[56:57] op_sel_hi:[1,0]
	s_waitcnt lgkmcnt(0)
	v_mfma_f32_16x16x32_bf16 v[40:43], v[44:47], v[32:35], v[40:43]
	v_mul_f32_e64 v14, v14, v56
	v_mul_f32_e64 v15, v15, v56
	v_pk_mul_f32 v[12:13], v[12:13], v[56:57] op_sel_hi:[1,0]
	v_pk_mul_f32 v[10:11], v[10:11], v[56:57] op_sel_hi:[1,0]
	s_nop 3
	v_cvt_pk_bf16_f32 v40, v40, s0
	ds_write_b16 v117, v40 offset:12784
	v_cvt_pk_bf16_f32 v40, v41, s0
	ds_write_b16 v117, v40 offset:13056
	v_cvt_pk_bf16_f32 v40, v42, s0
	ds_write_b16 v117, v40 offset:13328
	v_cvt_pk_bf16_f32 v40, v43, s0
	ds_write_b16 v117, v40 offset:13600
	ds_read_b128 v[40:43], v115 offset:44032
	s_waitcnt lgkmcnt(0)
	v_mfma_f32_16x16x32_bf16 v[28:31], v[40:43], v[36:39], v[28:31]
	ds_read_b128 v[40:43], v115 offset:44096
	v_pk_mul_f32 v[8:9], v[8:9], v[56:57] op_sel_hi:[1,0]
	v_pk_mul_f32 v[26:27], v[26:27], v[56:57] op_sel_hi:[1,0]
	s_waitcnt lgkmcnt(0)
	v_mfma_f32_16x16x32_bf16 v[28:31], v[40:43], v[32:35], v[28:31]
	ds_read_b128 v[40:43], v115 offset:46336
	v_pk_mul_f32 v[24:25], v[24:25], v[56:57] op_sel_hi:[1,0]
	s_waitcnt lgkmcnt(0)
	v_mfma_f32_16x16x32_bf16 v[20:23], v[40:43], v[36:39], v[20:23]
	ds_read_b128 v[40:43], v115 offset:46400
	s_waitcnt lgkmcnt(0)
	v_mfma_f32_16x16x32_bf16 v[20:23], v[40:43], v[32:35], v[20:23]
	ds_read_b128 v[40:43], v115 offset:48640
	s_waitcnt lgkmcnt(0)
	v_mfma_f32_16x16x32_bf16 v[0:3], v[40:43], v[36:39], v[0:3]
	ds_read_b128 v[40:43], v115 offset:48704
	s_waitcnt lgkmcnt(0)
	v_mfma_f32_16x16x32_bf16 v[0:3], v[40:43], v[32:35], v[0:3]
	ds_read_b128 v[40:43], v115 offset:50944
	s_waitcnt lgkmcnt(0)
	v_mfma_f32_16x16x32_bf16 v[16:19], v[40:43], v[36:39], v[16:19]
	ds_read_b128 v[40:43], v115 offset:51008
	s_waitcnt lgkmcnt(0)
	v_mfma_f32_16x16x32_bf16 v[16:19], v[40:43], v[32:35], v[16:19]
	ds_read_b128 v[40:43], v115 offset:53248
	s_waitcnt lgkmcnt(0)
	v_mfma_f32_16x16x32_bf16 v[4:7], v[40:43], v[36:39], v[4:7]
	ds_read_b128 v[40:43], v115 offset:53312
	s_waitcnt lgkmcnt(0)
	v_mfma_f32_16x16x32_bf16 v[4:7], v[40:43], v[32:35], v[4:7]
	ds_read_b128 v[40:43], v115 offset:55552
	s_waitcnt lgkmcnt(0)
	v_mfma_f32_16x16x32_bf16 v[12:15], v[40:43], v[36:39], v[12:15]
	ds_read_b128 v[40:43], v115 offset:55616
	s_waitcnt lgkmcnt(0)
	v_mfma_f32_16x16x32_bf16 v[12:15], v[40:43], v[32:35], v[12:15]
	ds_read_b128 v[40:43], v115 offset:57856
	s_waitcnt lgkmcnt(0)
	v_mfma_f32_16x16x32_bf16 v[8:11], v[40:43], v[36:39], v[8:11]
	ds_read_b128 v[40:43], v115 offset:57920
	s_waitcnt lgkmcnt(0)
	v_mfma_f32_16x16x32_bf16 v[8:11], v[40:43], v[32:35], v[8:11]
	ds_read_b128 v[40:43], v115 offset:60160
	s_waitcnt lgkmcnt(0)
	v_mfma_f32_16x16x32_bf16 v[24:27], v[40:43], v[36:39], v[24:27]
	ds_read_b128 v[36:39], v115 offset:60224
	s_waitcnt lgkmcnt(0)
	s_barrier
	v_mfma_f32_16x16x32_bf16 v[24:27], v[36:39], v[32:35], v[24:27]
	v_add_u32_e32 v36, v66, v68
	v_cvt_pk_bf16_f32 v32, v28, v29
	v_cvt_pk_bf16_f32 v33, v30, v31
	v_cvt_pk_bf16_f32 v34, v20, v21
	v_cvt_pk_bf16_f32 v35, v22, v23
	v_add_u32_e32 v36, 0xf000, v36
	ds_write2_b64 v36, v[32:33], v[34:35] offset0:128 offset1:132
	v_cvt_pk_bf16_f32 v32, v0, v1
	v_cvt_pk_bf16_f32 v33, v2, v3
	v_cvt_pk_bf16_f32 v34, v16, v17
	v_cvt_pk_bf16_f32 v35, v18, v19
	ds_write2_b64 v36, v[32:33], v[34:35] offset0:136 offset1:140
	v_cvt_pk_bf16_f32 v32, v4, v5
	v_cvt_pk_bf16_f32 v33, v6, v7
	v_cvt_pk_bf16_f32 v34, v12, v13
	v_cvt_pk_bf16_f32 v35, v14, v15
	ds_write2_b64 v36, v[32:33], v[34:35] offset0:144 offset1:148
	v_cvt_pk_bf16_f32 v32, v8, v9
	v_cvt_pk_bf16_f32 v33, v10, v11
	v_cvt_pk_bf16_f32 v34, v24, v25
	v_cvt_pk_bf16_f32 v35, v26, v27
	ds_write2_b64 v36, v[32:33], v[34:35] offset0:152 offset1:156
	s_and_saveexec_b64 s[30:31], s[40:41]
	s_cbranch_execz .LBB0_1097
	v_and_b32_e32 v32, 64, v164
	v_add_u32_e32 v32, 64, v32
	v_xor_b32_e32 v33, 1, v164
	v_cmp_lt_i32_e32 vcc, v33, v32
	ds_read_b128 v[52:55], v118
	ds_read_b128 v[60:63], v118 offset:16
	v_cndmask_b32_e32 v33, v164, v33, vcc
	v_lshlrev_b32_e32 v121, 2, v33
	v_xor_b32_e32 v33, 2, v164
	v_cmp_lt_i32_e32 vcc, v33, v32
	s_waitcnt lgkmcnt(0)
	v_lshlrev_b32_e32 v80, 16, v62
	v_and_b32_e32 v81, 0xffff0000, v62
	v_cndmask_b32_e32 v33, v164, v33, vcc
	v_lshlrev_b32_e32 v120, 2, v33
	v_xor_b32_e32 v33, 4, v164
	v_cmp_lt_i32_e32 vcc, v33, v32
	v_lshlrev_b32_e32 v78, 16, v63
	v_and_b32_e32 v79, 0xffff0000, v63
	v_cndmask_b32_e32 v32, v164, v33, vcc
	v_lshlrev_b32_e32 v119, 2, v32
	v_lshl_add_u32 v32, s0, 6, v112
	v_ashrrev_i32_e32 v33, 31, v32
	v_lshlrev_b64 v[76:77], 12, v[32:33]
	v_lshl_or_b32 v76, v70, 1, v76
	v_lshl_add_u64 v[32:33], s[46:47], 0, v[76:77]
	global_load_dwordx4 v[56:59], v[32:33], off
	s_nop 0
	global_load_dwordx4 v[32:35], v[32:33], off offset:16
	s_nop 0
	global_load_dwordx4 v[36:39], v[74:75], off offset:48
	global_load_dwordx4 v[40:43], v[74:75], off offset:32
	global_load_dwordx4 v[44:47], v[74:75], off offset:16
	global_load_dwordx4 v[48:51], v[74:75], off
	v_pk_mul_f32 v[62:63], v[80:81], v[80:81]
	v_pk_mul_f32 v[82:83], v[78:79], v[78:79]
	s_waitcnt vmcnt(5)
	v_lshlrev_b32_e32 v130, 16, v56
	s_waitcnt vmcnt(4)
	v_lshlrev_b32_e32 v84, 16, v34
	v_and_b32_e32 v85, 0xffff0000, v34
	v_mul_f32_e32 v34, 0xbfb8aa3b, v84
	v_exp_f32_e32 v86, v34
	v_mul_f32_e32 v34, 0xbfb8aa3b, v85
	v_exp_f32_e32 v87, v34
	v_and_b32_e32 v131, 0xffff0000, v56
	v_pk_add_f32 v[86:87], v[86:87], 1.0 op_sel_hi:[1,0]
	s_nop 0
	s_nop 0
	v_rcp_f32_e32 v87, v87
	s_nop 0
	s_nop 0
	v_lshlrev_b32_e32 v88, 16, v33
	v_and_b32_e32 v89, 0xffff0000, v33
	v_mul_f32_e32 v33, 0xbfb8aa3b, v88
	v_exp_f32_e32 v90, v33
	v_mul_f32_e32 v33, 0xbfb8aa3b, v89
	v_exp_f32_e32 v91, v33
	v_rcp_f32_e32 v86, v86
	s_nop 0
	v_pk_mul_f32 v[84:85], v[86:87], v[84:85]
	v_lshlrev_b32_e32 v86, 16, v61
	v_pk_add_f32 v[90:91], v[90:91], 1.0 op_sel_hi:[1,0]
	v_and_b32_e32 v87, 0xffff0000, v61
	v_pk_mul_f32 v[92:93], v[86:87], v[86:87]
	v_rcp_f32_e32 v91, v91
	s_nop 0
	s_nop 0
	v_lshlrev_b32_e32 v94, 16, v32
	v_and_b32_e32 v95, 0xffff0000, v32
	v_rcp_f32_e32 v90, v90
	s_nop 0
	v_mul_f32_e32 v32, 0xbfb8aa3b, v94
	v_mul_f32_e32 v33, 0xbfb8aa3b, v95
	v_exp_f32_e32 v32, v32
	v_exp_f32_e32 v33, v33
	v_pk_mul_f32 v[88:89], v[90:91], v[88:89]
	v_lshlrev_b32_e32 v90, 16, v60
	v_and_b32_e32 v91, 0xffff0000, v60
	v_pk_add_f32 v[32:33], v[32:33], 1.0 op_sel_hi:[1,0]
	v_pk_mul_f32 v[60:61], v[90:91], v[90:91]
	s_nop 0
	v_rcp_f32_e32 v33, v33
	s_nop 0
	s_nop 0
	v_lshlrev_b32_e32 v98, 16, v59
	v_rcp_f32_e32 v32, v32
	s_nop 0
	v_and_b32_e32 v99, 0xffff0000, v59
	v_mul_f32_e32 v34, 0xbfb8aa3b, v98
	v_exp_f32_e32 v100, v34
	v_mul_f32_e32 v34, 0xbfb8aa3b, v99
	v_exp_f32_e32 v101, v34
	v_pk_mul_f32 v[32:33], v[32:33], v[94:95]
	v_lshlrev_b32_e32 v94, 16, v55
	v_and_b32_e32 v95, 0xffff0000, v55
	v_pk_add_f32 v[100:101], v[100:101], 1.0 op_sel_hi:[1,0]
	v_pk_mul_f32 v[96:97], v[94:95], v[94:95]
	s_nop 0
	v_rcp_f32_e32 v101, v101
	s_nop 0
	s_nop 0
	v_lshlrev_b32_e32 v102, 16, v58
	v_rcp_f32_e32 v100, v100
	s_nop 0
	v_and_b32_e32 v103, 0xffff0000, v58
	v_mul_f32_e32 v34, 0xbfb8aa3b, v102
	v_exp_f32_e32 v58, v34
	v_mul_f32_e32 v34, 0xbfb8aa3b, v103
	v_exp_f32_e32 v59, v34
	v_pk_mul_f32 v[98:99], v[100:101], v[98:99]
	v_lshlrev_b32_e32 v100, 16, v54
	v_and_b32_e32 v101, 0xffff0000, v54
	v_pk_add_f32 v[58:59], v[58:59], 1.0 op_sel_hi:[1,0]
	v_pk_mul_f32 v[54:55], v[100:101], v[100:101]
	s_nop 0
	v_rcp_f32_e32 v59, v59
	s_nop 0
	s_nop 0
	v_lshlrev_b32_e32 v106, 16, v57
	v_rcp_f32_e32 v58, v58
	s_nop 0
	v_and_b32_e32 v107, 0xffff0000, v57
	v_mul_f32_e32 v34, 0xbfb8aa3b, v106
	v_exp_f32_e32 v122, v34
	v_mul_f32_e32 v34, 0xbfb8aa3b, v107
	v_exp_f32_e32 v123, v34
	v_pk_mul_f32 v[58:59], v[58:59], v[102:103]
	v_lshlrev_b32_e32 v102, 16, v53
	v_and_b32_e32 v103, 0xffff0000, v53
	v_pk_add_f32 v[122:123], v[122:123], 1.0 op_sel_hi:[1,0]
	v_pk_mul_f32 v[104:105], v[102:103], v[102:103]
	s_nop 0
	v_rcp_f32_e32 v123, v123
	s_nop 0
	s_nop 0
	v_rcp_f32_e32 v122, v122
	s_nop 0
	v_mul_f32_e32 v34, 0xbfb8aa3b, v130
	v_exp_f32_e32 v56, v34
	v_mul_f32_e32 v34, 0xbfb8aa3b, v131
	v_exp_f32_e32 v57, v34
	v_pk_mul_f32 v[106:107], v[122:123], v[106:107]
	v_lshlrev_b32_e32 v122, 16, v52
	v_and_b32_e32 v123, 0xffff0000, v52
	v_pk_add_f32 v[56:57], v[56:57], 1.0 op_sel_hi:[1,0]
	v_pk_mul_f32 v[52:53], v[122:123], v[122:123]
	s_nop 0
	v_rcp_f32_e32 v57, v57
	s_nop 0
	s_nop 0
	v_rcp_f32_e32 v56, v56
	s_nop 0
	v_add_f32_e32 v34, v52, v53
	v_add_f32_e32 v34, v104, v34
	v_add_f32_e32 v34, v105, v34
	v_add_f32_e32 v34, v54, v34
	v_add_f32_e32 v34, v55, v34
	v_add_f32_e32 v34, v96, v34
	v_add_f32_e32 v34, v97, v34
	v_add_f32_e32 v34, v60, v34
	v_add_f32_e32 v34, v61, v34
	v_add_f32_e32 v34, v92, v34
	v_add_f32_e32 v34, v93, v34
	v_add_f32_e32 v34, v62, v34
	v_add_f32_e32 v34, v63, v34
	v_add_f32_e32 v34, v82, v34
	v_add_f32_e32 v34, v83, v34
	ds_bpermute_b32 v52, v121, v34
	v_pk_mul_f32 v[56:57], v[56:57], v[130:131]
	s_waitcnt lgkmcnt(0)
	v_add_f32_e32 v34, v34, v52
	ds_bpermute_b32 v52, v120, v34
	s_waitcnt lgkmcnt(0)
	v_add_f32_e32 v34, v34, v52
	ds_bpermute_b32 v52, v119, v34
	s_waitcnt lgkmcnt(0)
	v_add_f32_e32 v34, v34, v52
	v_fmamk_f32 v34, v34, 0x3c000000, v162
	v_cmp_gt_f32_e32 vcc, s6, v34
	v_mul_f32_e32 v52, 0x4b800000, v34
	s_nop 0
	v_cndmask_b32_e32 v34, v34, v52, vcc
	v_rsq_f32_e32 v34, v34
	s_nop 0
	v_mul_f32_e32 v52, 0x45800000, v34
	v_cndmask_b32_e32 v52, v34, v52, vcc
	v_pk_mul_f32 v[54:55], v[52:53], v[122:123] op_sel_hi:[0,1]
	s_waitcnt vmcnt(0)
	v_pk_mul_f32 v[48:49], v[48:49], v[54:55]
	v_pk_mul_f32 v[54:55], v[52:53], v[102:103] op_sel_hi:[0,1]
	v_pk_mul_f32 v[50:51], v[50:51], v[54:55]
	v_pk_mul_f32 v[48:49], v[56:57], v[48:49]
	v_pk_mul_f32 v[50:51], v[106:107], v[50:51]
	v_cvt_pk_bf16_f32 v48, v48, v49
	v_cvt_pk_bf16_f32 v49, v50, v51
	v_pk_mul_f32 v[50:51], v[52:53], v[100:101] op_sel_hi:[0,1]
	v_pk_mul_f32 v[44:45], v[44:45], v[50:51]
	s_nop 0
	v_pk_mul_f32 v[44:45], v[58:59], v[44:45]
	s_nop 0
	v_cvt_pk_bf16_f32 v50, v44, v45
	v_pk_mul_f32 v[44:45], v[52:53], v[94:95] op_sel_hi:[0,1]
	v_pk_mul_f32 v[44:45], v[46:47], v[44:45]
	s_nop 0
	v_pk_mul_f32 v[44:45], v[98:99], v[44:45]
	s_nop 0
	v_cvt_pk_bf16_f32 v51, v44, v45
	v_pk_mul_f32 v[44:45], v[52:53], v[90:91] op_sel_hi:[0,1]
	v_pk_mul_f32 v[40:41], v[40:41], v[44:45]
	s_nop 0
	v_pk_mul_f32 v[32:33], v[32:33], v[40:41]
	v_pk_mul_f32 v[40:41], v[52:53], v[86:87] op_sel_hi:[0,1]
	v_pk_mul_f32 v[40:41], v[42:43], v[40:41]
	v_cvt_pk_bf16_f32 v32, v32, v33
	v_pk_mul_f32 v[40:41], v[88:89], v[40:41]
	v_pk_mul_f32 v[42:43], v[52:53], v[78:79] op_sel_hi:[0,1]
	v_cvt_pk_bf16_f32 v33, v40, v41
	v_pk_mul_f32 v[40:41], v[52:53], v[80:81] op_sel_hi:[0,1]
	v_pk_mul_f32 v[36:37], v[36:37], v[40:41]
	v_pk_mul_f32 v[38:39], v[38:39], v[42:43]
	v_pk_mul_f32 v[36:37], v[84:85], v[36:37]
	s_nop 0
	v_cvt_pk_bf16_f32 v34, v36, v37
	v_lshlrev_b32_e32 v36, 16, v35
	v_and_b32_e32 v37, 0xffff0000, v35
	v_mul_f32_e32 v35, 0xbfb8aa3b, v36
	v_exp_f32_e32 v40, v35
	v_mul_f32_e32 v35, 0xbfb8aa3b, v37
	v_exp_f32_e32 v41, v35
	s_nop 0
	v_pk_add_f32 v[40:41], v[40:41], 1.0 op_sel_hi:[1,0]
	s_nop 0
	s_nop 0
	v_rcp_f32_e32 v41, v41
	s_nop 0
	s_nop 0
	v_rcp_f32_e32 v40, v40
	s_nop 0
	v_pk_mul_f32 v[36:37], v[40:41], v[36:37]
	s_nop 0
	v_pk_mul_f32 v[36:37], v[36:37], v[38:39]
	s_nop 0
	v_cvt_pk_bf16_f32 v35, v36, v37
	v_lshl_add_u64 v[36:37], s[48:49], 0, v[76:77]
	global_store_dwordx4 v[36:37], v[48:51], off
	global_store_dwordx4 v[36:37], v[32:35], off offset:16
	s_branch .LBB0_1097
